# P1: cheap tiles in last round + all workgroups backfill deferred transposes at the end of P1 (balanced split)
# baseline (speedup 1.0000x reference)
; #define LAS __attribute__((address_space(3)))
; #define INP(i) ((const float*)(const GAS float*)KARG(8 * (i)))
; template <int KIND> __device__ __forceinline__ void tr_item(const float* __restrict__ W, int K, int Nsrc, const float* __restrict__ gk, bf16_t* WT, LAS float* scr, int item, int nblk, int lane) {
;     const int kb = item / nblk, nb = item - kb * nblk, k0 = 64 * kb, n0 = 32 * nb;
;     const int src = srcmap<KIND>(n0 + (lane & 31));
; #pragma unroll 8
;     for (int i = 0; i < 32; ++i) { const int kk = 2 * i + (lane >> 5); float v = 0.f; if (src >= 0) v = __builtin_nontemporal_load(&W[(size_t)(k0 + kk) * Nsrc + src]); if (gk) v *= gk[k0 + kk]; scr[kk * 33 + (lane & 31)] = v; }
; __global__ void __launch_bounds__(512, 2) fwd(Params P) {
;     ...
;         for (int it = gw; it < NITEMS; it += NGW) {
;             int r = it;
;             if (r < I0) { tr_item<1>(INP(4), 2048, 8256, nullptr, wb + OFF_WIN, scr, r, NIN / 32, lane); continue; } r -= I0;
;             if (r < I1) { tr_item<2>(INP(7), 512, 1536, INP(5), wb + OFF_WQ, scr, r, 1536 / 32, lane); continue; } r -= I1;
;             if (r < I2) { tr_item<0>(INP(8), 512, 2048, INP(6), wb + OFF_WKV, scr, r, 2048 / 32, lane); continue; } r -= I2;
;             if (r < I3) { tr_item<0>(INP(9), 1024, 2048, nullptr, wb + OFF_WSBO, scr, r, 2048 / 32, lane); continue; } r -= I3;
;             if (r < I4) { tr_item<0>(INP(10), 1024, 2048, nullptr, wb + OFF_WMLAO, scr, r, 2048 / 32, lane); continue; } r -= I4;
;             if (r < I5) { tr_item<0>(INP(11), 2048, 2048, nullptr, wb + OFF_WOUT, scr, r, 2048 / 32, lane); continue; } r -= I5;
;             if (r < I6) { tr_item<0>(INP(14), 2048, 8192, nullptr, wb + OFF_WUP, scr, r, 8192 / 32, lane); continue; } r -= I6;
;             if (r < I7) { tr_item<0>(INP(15), 8192, 2048, nullptr, wb + OFF_WDOWN, scr, r, 2048 / 32, lane); continue; } r -= I7;
;             if (r < I8) { tr_item<0>(INP(17), 256, 2048, nullptr, wb + OFF_WPLE, scr, r, 2048 / 32, lane); continue; } r -= I8;
;             tr_item<0>(INP(19), 2048, 2048, nullptr, wb + OFF_WPG, scr, r, 2048 / 32, lane);
.LBB0_501:
	s_andn2_b64 vcc, exec, s[22:23]
	s_cbranch_vccnz .LBB0_212
	s_barrier
	s_branch .LBB0_212
.LBB0_503:
	s_waitcnt vmcnt(0)
	s_barrier
.Lp1t_entry:
	v_readfirstlane_b32 s32, v178
	s_load_dwordx2 s[20:21], s[0:1], 0xa8
	v_lshrrev_b32_e32 v0, 5, v179
	v_and_b32_e32 v1, 31, v179
	v_lshrrev_b32_e32 v2, 3, v179
	v_and_b32_e32 v3, 7, v179
	s_lshr_b32 s32, s32, 6
	s_lshl_b32 s32, s32, 14
	v_lshlrev_b32_e32 v1, 2, v1
	v_mul_u32_u24_e32 v4, 0x84, v0
	v_mul_u32_u24_e32 v5, 0x420, v3
	v_add3_u32 v4, v4, v1, s32
	v_lshl_add_u32 v5, v2, 2, v5
	v_add_u32_e32 v5, s32, v5
	v_lshlrev_b32_e32 v3, 4, v3
	s_cmp_lt_u32 s84, 0x80
	s_mov_b32 s33, 0x757f
	s_cselect_b32 s33, 0x7d7f, s33
	s_mov_b32 s5, 0x5480
	s_cselect_b32 s5, 0x7580, s5
	s_and_b32 s4, s84, 0x7f
	s_lshl_b32 s4, s4, 3
	s_add_i32 s4, s4, s5
	s_lshr_b32 s5, s32, 14
	s_add_i32 s4, s4, s5
	s_waitcnt lgkmcnt(0)
	s_add_u32 s20, s20, 0x100000
	s_addc_u32 s21, s21, 0
	s_mov_b32 s16, 0x7580
	s_movk_i32 s15, 0x98
	s_mov_b32 s11, 13
	s_mov_b32 s12, 6
	s_mov_b32 s13, 11
	s_mov_b32 s14, 61603840
	s_cmpk_lt_u32 s4, 0x7580
	s_cselect_b32 s16, 0x7480, s16
	s_cselect_b32 s15, 0x88, s15
	s_cselect_b32 s11, 13, s11
	s_cselect_b32 s12, 6, s12
	s_cselect_b32 s13, 8, s13
	s_cselect_b32 s14, 61079552, s14
	s_cmpk_lt_u32 s4, 0x7480
	s_cselect_b32 s16, 0x5480, s16
	s_cselect_b32 s15, 0x78, s15
	s_cselect_b32 s11, 13, s11
	s_cselect_b32 s12, 6, s12
	s_cselect_b32 s13, 13, s13
	s_cselect_b32 s14, 44302336, s14
	s_cmpk_lt_u32 s4, 0x5480
	s_cselect_b32 s16, 0x3480, s16
	s_cselect_b32 s15, 0x70, s15
	s_cselect_b32 s11, 15, s11
	s_cselect_b32 s12, 8, s12
	s_cselect_b32 s13, 11, s13
	s_cselect_b32 s14, 27525120, s14
	s_cmpk_lt_u32 s4, 0x3480
	s_cselect_b32 s16, 0x2c80, s16
	s_cselect_b32 s15, 0x58, s15
	s_cselect_b32 s11, 13, s11
	s_cselect_b32 s12, 6, s12
	s_cselect_b32 s13, 11, s13
	s_cselect_b32 s14, 23330816, s14
	s_cmpk_lt_u32 s4, 0x2c80
	s_cselect_b32 s16, 0x2880, s16
	s_cselect_b32 s15, 0x50, s15
	s_cselect_b32 s11, 13, s11
	s_cselect_b32 s12, 6, s12
	s_cselect_b32 s13, 10, s13
	s_cselect_b32 s14, 21233664, s14
	s_cmpk_lt_u32 s4, 0x2880
	s_cselect_b32 s16, 0x2480, s16
	s_cselect_b32 s15, 0x48, s15
	s_cselect_b32 s11, 13, s11
	s_cselect_b32 s12, 6, s12
	s_cselect_b32 s13, 10, s13
	s_cselect_b32 s14, 19136512, s14
	s_load_dwordx2 s[6:7], s[0:1], s15
	s_sub_i32 s16, s4, s16
	s_lshl_b32 s19, 1, s12
	s_sub_i32 s19, s19, 1
	s_and_b32 s18, s16, s19
	s_lshr_b32 s17, s16, s12
	s_lshl_b32 s17, s17, 6
	s_lshl_b32 s19, s17, s11
	s_lshl_b32 s29, s18, 7
	s_add_u32 s19, s19, s29
	s_lshl_b32 s10, 2, s11
	v_lshlrev_b32_e32 v6, s11, v0
	v_add_u32_e32 v6, v6, v1
	s_lshl_b32 s29, s18, 5
	s_lshl_b32 s29, s29, s13
	s_add_u32 s29, s29, s17
	s_add_u32 s29, s29, s14
	s_lshl_b32 s29, s29, 1
	s_add_u32 s22, s20, s29
	s_addc_u32 s23, s21, 0
	s_lshl_b32 s24, 16, s13
	s_add_i32 s29, s13, 1
	v_lshlrev_b32_e32 v8, s29, v2
	v_add_u32_e32 v8, v8, v3
	s_waitcnt lgkmcnt(0)
	s_add_u32 s8, s6, s19
	s_addc_u32 s9, s7, 0
	global_load_dword v32, v6, s[8:9] nt
	s_add_u32 s8, s8, s10
	s_addc_u32 s9, s9, 0
	global_load_dword v33, v6, s[8:9] nt
	s_add_u32 s8, s8, s10
	s_addc_u32 s9, s9, 0
	global_load_dword v34, v6, s[8:9] nt
	s_add_u32 s8, s8, s10
	s_addc_u32 s9, s9, 0
	global_load_dword v35, v6, s[8:9] nt
	s_add_u32 s8, s8, s10
	s_addc_u32 s9, s9, 0
	global_load_dword v36, v6, s[8:9] nt
	s_add_u32 s8, s8, s10
	s_addc_u32 s9, s9, 0
	global_load_dword v37, v6, s[8:9] nt
	s_add_u32 s8, s8, s10
	s_addc_u32 s9, s9, 0
	global_load_dword v38, v6, s[8:9] nt
	s_add_u32 s8, s8, s10
	s_addc_u32 s9, s9, 0
	global_load_dword v39, v6, s[8:9] nt
	s_add_u32 s8, s8, s10
	s_addc_u32 s9, s9, 0
	global_load_dword v40, v6, s[8:9] nt
	s_add_u32 s8, s8, s10
	s_addc_u32 s9, s9, 0
	global_load_dword v41, v6, s[8:9] nt
	s_add_u32 s8, s8, s10
	s_addc_u32 s9, s9, 0
	global_load_dword v42, v6, s[8:9] nt
	s_add_u32 s8, s8, s10
	s_addc_u32 s9, s9, 0
	global_load_dword v43, v6, s[8:9] nt
	s_add_u32 s8, s8, s10
	s_addc_u32 s9, s9, 0
	global_load_dword v44, v6, s[8:9] nt
	s_add_u32 s8, s8, s10
	s_addc_u32 s9, s9, 0
	global_load_dword v45, v6, s[8:9] nt
	s_add_u32 s8, s8, s10
	s_addc_u32 s9, s9, 0
	global_load_dword v46, v6, s[8:9] nt
	s_add_u32 s8, s8, s10
	s_addc_u32 s9, s9, 0
	global_load_dword v47, v6, s[8:9] nt
	s_add_u32 s8, s8, s10
	s_addc_u32 s9, s9, 0
	global_load_dword v48, v6, s[8:9] nt
	s_add_u32 s8, s8, s10
	s_addc_u32 s9, s9, 0
	global_load_dword v49, v6, s[8:9] nt
	s_add_u32 s8, s8, s10
	s_addc_u32 s9, s9, 0
	global_load_dword v50, v6, s[8:9] nt
	s_add_u32 s8, s8, s10
	s_addc_u32 s9, s9, 0
	global_load_dword v51, v6, s[8:9] nt
	s_add_u32 s8, s8, s10
	s_addc_u32 s9, s9, 0
	global_load_dword v52, v6, s[8:9] nt
	s_add_u32 s8, s8, s10
	s_addc_u32 s9, s9, 0
	global_load_dword v53, v6, s[8:9] nt
	s_add_u32 s8, s8, s10
	s_addc_u32 s9, s9, 0
	global_load_dword v54, v6, s[8:9] nt
	s_add_u32 s8, s8, s10
	s_addc_u32 s9, s9, 0
	global_load_dword v55, v6, s[8:9] nt
	s_add_u32 s8, s8, s10
	s_addc_u32 s9, s9, 0
	global_load_dword v56, v6, s[8:9] nt
	s_add_u32 s8, s8, s10
	s_addc_u32 s9, s9, 0
	global_load_dword v57, v6, s[8:9] nt
	s_add_u32 s8, s8, s10
	s_addc_u32 s9, s9, 0
	global_load_dword v58, v6, s[8:9] nt
	s_add_u32 s8, s8, s10
	s_addc_u32 s9, s9, 0
	global_load_dword v59, v6, s[8:9] nt
	s_add_u32 s8, s8, s10
	s_addc_u32 s9, s9, 0
	global_load_dword v60, v6, s[8:9] nt
	s_add_u32 s8, s8, s10
	s_addc_u32 s9, s9, 0
	global_load_dword v61, v6, s[8:9] nt
	s_add_u32 s8, s8, s10
	s_addc_u32 s9, s9, 0
	global_load_dword v62, v6, s[8:9] nt
	s_add_u32 s8, s8, s10
	s_addc_u32 s9, s9, 0
	global_load_dword v63, v6, s[8:9] nt
	s_add_i32 s5, s4, 0x400
	s_cmp_gt_i32 s5, s33
	s_cbranch_scc1 .Lp1t_tail_a
; #define LAS __attribute__((address_space(3)))
; template <int KIND> __device__ __forceinline__ void tr_item(const float* __restrict__ W, int K, int Nsrc, const float* __restrict__ gk, bf16_t* WT, LAS float* scr, int item, int nblk, int lane) {
;     const int kb = item / nblk, nb = item - kb * nblk, k0 = 64 * kb, n0 = 32 * nb;
;     const int src = srcmap<KIND>(n0 + (lane & 31));
; #pragma unroll 8
;     for (int i = 0; i < 32; ++i) { const int kk = 2 * i + (lane >> 5); float v = 0.f; if (src >= 0) v = __builtin_nontemporal_load(&W[(size_t)(k0 + kk) * Nsrc + src]); if (gk) v *= gk[k0 + kk]; scr[kk * 33 + (lane & 31)] = v; }
;     asm volatile("s_waitcnt lgkmcnt(0)" ::: "memory");
;     const int c = lane & 7;
; #pragma unroll
;     for (int j = 0; j < 4; ++j) { const int n = (lane >> 3) + 8 * j; const LAS float* s = scr + (8 * c) * 33 + n;
	s_mov_b32 s16, 0x7580
	s_movk_i32 s15, 0x98
	s_mov_b32 s11, 13
	s_mov_b32 s12, 6
	s_mov_b32 s13, 11
	s_mov_b32 s14, 61603840
	s_cmpk_lt_u32 s5, 0x7580
	s_cselect_b32 s16, 0x7480, s16
	s_cselect_b32 s15, 0x88, s15
	s_cselect_b32 s11, 13, s11
	s_cselect_b32 s12, 6, s12
	s_cselect_b32 s13, 8, s13
	s_cselect_b32 s14, 61079552, s14
	s_cmpk_lt_u32 s5, 0x7480
	s_cselect_b32 s16, 0x5480, s16
	s_cselect_b32 s15, 0x78, s15
	s_cselect_b32 s11, 13, s11
	s_cselect_b32 s12, 6, s12
	s_cselect_b32 s13, 13, s13
	s_cselect_b32 s14, 44302336, s14
	s_cmpk_lt_u32 s5, 0x5480
	s_cselect_b32 s16, 0x3480, s16
	s_cselect_b32 s15, 0x70, s15
	s_cselect_b32 s11, 15, s11
	s_cselect_b32 s12, 8, s12
	s_cselect_b32 s13, 11, s13
	s_cselect_b32 s14, 27525120, s14
	s_cmpk_lt_u32 s5, 0x3480
	s_cselect_b32 s16, 0x2c80, s16
	s_cselect_b32 s15, 0x58, s15
	s_cselect_b32 s11, 13, s11
	s_cselect_b32 s12, 6, s12
	s_cselect_b32 s13, 11, s13
	s_cselect_b32 s14, 23330816, s14
	s_cmpk_lt_u32 s5, 0x2c80
	s_cselect_b32 s16, 0x2880, s16
	s_cselect_b32 s15, 0x50, s15
	s_cselect_b32 s11, 13, s11
	s_cselect_b32 s12, 6, s12
	s_cselect_b32 s13, 10, s13
	s_cselect_b32 s14, 21233664, s14
	s_cmpk_lt_u32 s5, 0x2880
	s_cselect_b32 s16, 0x2480, s16
	s_cselect_b32 s15, 0x48, s15
	s_cselect_b32 s11, 13, s11
	s_cselect_b32 s12, 6, s12
	s_cselect_b32 s13, 10, s13
	s_cselect_b32 s14, 19136512, s14
	s_load_dwordx2 s[6:7], s[0:1], s15
	s_sub_i32 s16, s5, s16
	s_lshl_b32 s19, 1, s12
	s_sub_i32 s19, s19, 1
	s_and_b32 s18, s16, s19
	s_lshr_b32 s17, s16, s12
	s_lshl_b32 s17, s17, 6
	s_lshl_b32 s19, s17, s11
	s_lshl_b32 s29, s18, 7
	s_add_u32 s19, s19, s29
	s_lshl_b32 s10, 2, s11
	v_lshlrev_b32_e32 v6, s11, v0
	v_add_u32_e32 v6, v6, v1
	s_lshl_b32 s29, s18, 5
	s_lshl_b32 s29, s29, s13
	s_add_u32 s29, s29, s17
	s_add_u32 s29, s29, s14
	s_lshl_b32 s29, s29, 1
	s_add_u32 s26, s20, s29
	s_addc_u32 s27, s21, 0
	s_lshl_b32 s28, 16, s13
	s_add_i32 s29, s13, 1
	v_lshlrev_b32_e32 v9, s29, v2
	v_add_u32_e32 v9, v9, v3
	s_waitcnt lgkmcnt(0)
	s_add_u32 s8, s6, s19
	s_addc_u32 s9, s7, 0
	global_load_dword v64, v6, s[8:9] nt
	s_add_u32 s8, s8, s10
	s_addc_u32 s9, s9, 0
	global_load_dword v65, v6, s[8:9] nt
	s_add_u32 s8, s8, s10
	s_addc_u32 s9, s9, 0
	global_load_dword v66, v6, s[8:9] nt
	s_add_u32 s8, s8, s10
	s_addc_u32 s9, s9, 0
	global_load_dword v67, v6, s[8:9] nt
	s_add_u32 s8, s8, s10
	s_addc_u32 s9, s9, 0
	global_load_dword v68, v6, s[8:9] nt
	s_add_u32 s8, s8, s10
	s_addc_u32 s9, s9, 0
	global_load_dword v69, v6, s[8:9] nt
	s_add_u32 s8, s8, s10
	s_addc_u32 s9, s9, 0
	global_load_dword v70, v6, s[8:9] nt
	s_add_u32 s8, s8, s10
	s_addc_u32 s9, s9, 0
	global_load_dword v71, v6, s[8:9] nt
	s_add_u32 s8, s8, s10
	s_addc_u32 s9, s9, 0
	global_load_dword v72, v6, s[8:9] nt
	s_add_u32 s8, s8, s10
	s_addc_u32 s9, s9, 0
	global_load_dword v73, v6, s[8:9] nt
	s_add_u32 s8, s8, s10
	s_addc_u32 s9, s9, 0
	global_load_dword v74, v6, s[8:9] nt
	s_add_u32 s8, s8, s10
	s_addc_u32 s9, s9, 0
	global_load_dword v75, v6, s[8:9] nt
	s_add_u32 s8, s8, s10
	s_addc_u32 s9, s9, 0
	global_load_dword v76, v6, s[8:9] nt
	s_add_u32 s8, s8, s10
	s_addc_u32 s9, s9, 0
	global_load_dword v77, v6, s[8:9] nt
	s_add_u32 s8, s8, s10
	s_addc_u32 s9, s9, 0
	global_load_dword v78, v6, s[8:9] nt
	s_add_u32 s8, s8, s10
	s_addc_u32 s9, s9, 0
	global_load_dword v79, v6, s[8:9] nt
	s_add_u32 s8, s8, s10
	s_addc_u32 s9, s9, 0
	global_load_dword v80, v6, s[8:9] nt
	s_add_u32 s8, s8, s10
	s_addc_u32 s9, s9, 0
	global_load_dword v81, v6, s[8:9] nt
	s_add_u32 s8, s8, s10
	s_addc_u32 s9, s9, 0
	global_load_dword v82, v6, s[8:9] nt
	s_add_u32 s8, s8, s10
	s_addc_u32 s9, s9, 0
	global_load_dword v83, v6, s[8:9] nt
	s_add_u32 s8, s8, s10
	s_addc_u32 s9, s9, 0
	global_load_dword v84, v6, s[8:9] nt
	s_add_u32 s8, s8, s10
	s_addc_u32 s9, s9, 0
	global_load_dword v85, v6, s[8:9] nt
	s_add_u32 s8, s8, s10
	s_addc_u32 s9, s9, 0
	global_load_dword v86, v6, s[8:9] nt
	s_add_u32 s8, s8, s10
	s_addc_u32 s9, s9, 0
	global_load_dword v87, v6, s[8:9] nt
	s_add_u32 s8, s8, s10
	s_addc_u32 s9, s9, 0
	global_load_dword v88, v6, s[8:9] nt
	s_add_u32 s8, s8, s10
	s_addc_u32 s9, s9, 0
	global_load_dword v89, v6, s[8:9] nt
	s_add_u32 s8, s8, s10
	s_addc_u32 s9, s9, 0
	global_load_dword v90, v6, s[8:9] nt
	s_add_u32 s8, s8, s10
	s_addc_u32 s9, s9, 0
	global_load_dword v91, v6, s[8:9] nt
	s_add_u32 s8, s8, s10
	s_addc_u32 s9, s9, 0
	global_load_dword v92, v6, s[8:9] nt
	s_add_u32 s8, s8, s10
	s_addc_u32 s9, s9, 0
	global_load_dword v93, v6, s[8:9] nt
	s_add_u32 s8, s8, s10
	s_addc_u32 s9, s9, 0
	global_load_dword v94, v6, s[8:9] nt
	s_add_u32 s8, s8, s10
	s_addc_u32 s9, s9, 0
	global_load_dword v95, v6, s[8:9] nt
	s_mov_b64 s[30:31], s[22:23]
	s_waitcnt vmcnt(63)
	ds_write_b32 v4, v32
	s_waitcnt vmcnt(62)
	ds_write_b32 v4, v33 offset:264
	s_waitcnt vmcnt(61)
	ds_write_b32 v4, v34 offset:528
	s_waitcnt vmcnt(60)
	ds_write_b32 v4, v35 offset:792
	s_waitcnt vmcnt(59)
	ds_write_b32 v4, v36 offset:1056
	s_waitcnt vmcnt(58)
	ds_write_b32 v4, v37 offset:1320
	s_waitcnt vmcnt(57)
	ds_write_b32 v4, v38 offset:1584
	s_waitcnt vmcnt(56)
	ds_write_b32 v4, v39 offset:1848
	s_waitcnt vmcnt(55)
	ds_write_b32 v4, v40 offset:2112
	s_waitcnt vmcnt(54)
	ds_write_b32 v4, v41 offset:2376
	s_waitcnt vmcnt(53)
	ds_write_b32 v4, v42 offset:2640
	s_waitcnt vmcnt(52)
	ds_write_b32 v4, v43 offset:2904
	s_waitcnt vmcnt(51)
	ds_write_b32 v4, v44 offset:3168
	s_waitcnt vmcnt(50)
	ds_write_b32 v4, v45 offset:3432
	s_waitcnt vmcnt(49)
	ds_write_b32 v4, v46 offset:3696
	s_waitcnt vmcnt(48)
	ds_write_b32 v4, v47 offset:3960
	s_waitcnt vmcnt(47)
	ds_write_b32 v4, v48 offset:4224
	s_waitcnt vmcnt(46)
; #define LAS __attribute__((address_space(3)))
; __device__ __forceinline__ unsigned pk2(float lo, float hi) { return pg8::cvt_pk_bf16(lo, hi); }
; template <int KIND> __device__ __forceinline__ void tr_item(const float* __restrict__ W, int K, int Nsrc, const float* __restrict__ gk, bf16_t* WT, LAS float* scr, int item, int nblk, int lane) {
;     ...
;     for (int i = 0; i < 32; ++i) { const int kk = 2 * i + (lane >> 5); float v = 0.f; if (src >= 0) v = __builtin_nontemporal_load(&W[(size_t)(k0 + kk) * Nsrc + src]); if (gk) v *= gk[k0 + kk]; scr[kk * 33 + (lane & 31)] = v; }
;     asm volatile("s_waitcnt lgkmcnt(0)" ::: "memory");
;     const int c = lane & 7;
; #pragma unroll
;     for (int j = 0; j < 4; ++j) { const int n = (lane >> 3) + 8 * j; const LAS float* s = scr + (8 * c) * 33 + n;
;         u32x4 o; o.x = pk2(s[0 * 33], s[1 * 33]); o.y = pk2(s[2 * 33], s[3 * 33]); o.z = pk2(s[4 * 33], s[5 * 33]); o.w = pk2(s[6 * 33], s[7 * 33]);
;         *(u32x4*)(WT + (size_t)(n0 + n) * K + k0 + 8 * c) = o; }
	ds_write_b32 v4, v49 offset:4488
	s_waitcnt vmcnt(45)
	ds_write_b32 v4, v50 offset:4752
	s_waitcnt vmcnt(44)
	ds_write_b32 v4, v51 offset:5016
	s_waitcnt vmcnt(43)
	ds_write_b32 v4, v52 offset:5280
	s_waitcnt vmcnt(42)
	ds_write_b32 v4, v53 offset:5544
	s_waitcnt vmcnt(41)
	ds_write_b32 v4, v54 offset:5808
	s_waitcnt vmcnt(40)
	ds_write_b32 v4, v55 offset:6072
	s_waitcnt vmcnt(39)
	ds_write_b32 v4, v56 offset:6336
	s_waitcnt vmcnt(38)
	ds_write_b32 v4, v57 offset:6600
	s_waitcnt vmcnt(37)
	ds_write_b32 v4, v58 offset:6864
	s_waitcnt vmcnt(36)
	ds_write_b32 v4, v59 offset:7128
	s_waitcnt vmcnt(35)
	ds_write_b32 v4, v60 offset:7392
	s_waitcnt vmcnt(34)
	ds_write_b32 v4, v61 offset:7656
	s_waitcnt vmcnt(33)
	ds_write_b32 v4, v62 offset:7920
	s_waitcnt vmcnt(32)
	ds_write_b32 v4, v63 offset:8184
	s_waitcnt lgkmcnt(0)
	ds_read2_b32 v[96:97], v5 offset0:0 offset1:8
	ds_read2_b32 v[98:99], v5 offset0:16 offset1:24
	ds_read2_b32 v[100:101], v5 offset0:33 offset1:41
	ds_read2_b32 v[102:103], v5 offset0:49 offset1:57
	ds_read2_b32 v[104:105], v5 offset0:66 offset1:74
	ds_read2_b32 v[106:107], v5 offset0:82 offset1:90
	ds_read2_b32 v[108:109], v5 offset0:99 offset1:107
	ds_read2_b32 v[110:111], v5 offset0:115 offset1:123
	ds_read2_b32 v[112:113], v5 offset0:132 offset1:140
	ds_read2_b32 v[114:115], v5 offset0:148 offset1:156
	ds_read2_b32 v[116:117], v5 offset0:165 offset1:173
	ds_read2_b32 v[118:119], v5 offset0:181 offset1:189
	ds_read2_b32 v[120:121], v5 offset0:198 offset1:206
	ds_read2_b32 v[122:123], v5 offset0:214 offset1:222
	ds_read2_b32 v[124:125], v5 offset0:231 offset1:239
	ds_read2_b32 v[126:127], v5 offset0:247 offset1:255
	s_waitcnt lgkmcnt(0)
	v_cvt_pk_bf16_f32 v12, v96, v100
	v_cvt_pk_bf16_f32 v13, v104, v108
	v_cvt_pk_bf16_f32 v14, v112, v116
	v_cvt_pk_bf16_f32 v15, v120, v124
	global_store_dwordx4 v8, v[12:15], s[30:31]
	s_add_u32 s30, s30, s24
	s_addc_u32 s31, s31, 0
	v_cvt_pk_bf16_f32 v16, v97, v101
	v_cvt_pk_bf16_f32 v17, v105, v109
	v_cvt_pk_bf16_f32 v18, v113, v117
	v_cvt_pk_bf16_f32 v19, v121, v125
	global_store_dwordx4 v8, v[16:19], s[30:31]
	s_add_u32 s30, s30, s24
	s_addc_u32 s31, s31, 0
	v_cvt_pk_bf16_f32 v12, v98, v102
	v_cvt_pk_bf16_f32 v13, v106, v110
	v_cvt_pk_bf16_f32 v14, v114, v118
	v_cvt_pk_bf16_f32 v15, v122, v126
	global_store_dwordx4 v8, v[12:15], s[30:31]
	s_add_u32 s30, s30, s24
	s_addc_u32 s31, s31, 0
	v_cvt_pk_bf16_f32 v16, v99, v103
	v_cvt_pk_bf16_f32 v17, v107, v111
	v_cvt_pk_bf16_f32 v18, v115, v119
	v_cvt_pk_bf16_f32 v19, v123, v127
	global_store_dwordx4 v8, v[16:19], s[30:31]
	s_mov_b32 s4, s5
.Lp1t_loop:
	s_add_i32 s5, s4, 0x400
	s_cmp_gt_i32 s5, s33
	s_cbranch_scc1 .Lp1t_tail_b
	s_mov_b32 s16, 0x7580
	s_movk_i32 s15, 0x98
	s_mov_b32 s11, 13
	s_mov_b32 s12, 6
	s_mov_b32 s13, 11
	s_mov_b32 s14, 61603840
	s_cmpk_lt_u32 s5, 0x7580
	s_cselect_b32 s16, 0x7480, s16
	s_cselect_b32 s15, 0x88, s15
	s_cselect_b32 s11, 13, s11
	s_cselect_b32 s12, 6, s12
	s_cselect_b32 s13, 8, s13
	s_cselect_b32 s14, 61079552, s14
	s_cmpk_lt_u32 s5, 0x7480
	s_cselect_b32 s16, 0x5480, s16
	s_cselect_b32 s15, 0x78, s15
	s_cselect_b32 s11, 13, s11
	s_cselect_b32 s12, 6, s12
	s_cselect_b32 s13, 13, s13
	s_cselect_b32 s14, 44302336, s14
	s_cmpk_lt_u32 s5, 0x5480
	s_cselect_b32 s16, 0x3480, s16
	s_cselect_b32 s15, 0x70, s15
	s_cselect_b32 s11, 15, s11
	s_cselect_b32 s12, 8, s12
	s_cselect_b32 s13, 11, s13
	s_cselect_b32 s14, 27525120, s14
	s_cmpk_lt_u32 s5, 0x3480
	s_cselect_b32 s16, 0x2c80, s16
	s_cselect_b32 s15, 0x58, s15
	s_cselect_b32 s11, 13, s11
	s_cselect_b32 s12, 6, s12
	s_cselect_b32 s13, 11, s13
	s_cselect_b32 s14, 23330816, s14
	s_cmpk_lt_u32 s5, 0x2c80
	s_cselect_b32 s16, 0x2880, s16
	s_cselect_b32 s15, 0x50, s15
	s_cselect_b32 s11, 13, s11
	s_cselect_b32 s12, 6, s12
	s_cselect_b32 s13, 10, s13
	s_cselect_b32 s14, 21233664, s14
	s_cmpk_lt_u32 s5, 0x2880
	s_cselect_b32 s16, 0x2480, s16
	s_cselect_b32 s15, 0x48, s15
	s_cselect_b32 s11, 13, s11
	s_cselect_b32 s12, 6, s12
	s_cselect_b32 s13, 10, s13
	s_cselect_b32 s14, 19136512, s14
	s_load_dwordx2 s[6:7], s[0:1], s15
	s_sub_i32 s16, s5, s16
	s_lshl_b32 s19, 1, s12
	s_sub_i32 s19, s19, 1
	s_and_b32 s18, s16, s19
	s_lshr_b32 s17, s16, s12
	s_lshl_b32 s17, s17, 6
	s_lshl_b32 s19, s17, s11
	s_lshl_b32 s29, s18, 7
	s_add_u32 s19, s19, s29
	s_lshl_b32 s10, 2, s11
	v_lshlrev_b32_e32 v6, s11, v0
	v_add_u32_e32 v6, v6, v1
	s_lshl_b32 s29, s18, 5
	s_lshl_b32 s29, s29, s13
	s_add_u32 s29, s29, s17
	s_add_u32 s29, s29, s14
	s_lshl_b32 s29, s29, 1
	s_add_u32 s22, s20, s29
	s_addc_u32 s23, s21, 0
	s_lshl_b32 s24, 16, s13
	s_add_i32 s29, s13, 1
	v_lshlrev_b32_e32 v8, s29, v2
	v_add_u32_e32 v8, v8, v3
	s_waitcnt lgkmcnt(0)
; #define LAS __attribute__((address_space(3)))
; __device__ __forceinline__ unsigned pk2(float lo, float hi) { return pg8::cvt_pk_bf16(lo, hi); }
; template <int KIND> __device__ __forceinline__ void tr_item(const float* __restrict__ W, int K, int Nsrc, const float* __restrict__ gk, bf16_t* WT, LAS float* scr, int item, int nblk, int lane) {
;     ...
;     for (int i = 0; i < 32; ++i) { const int kk = 2 * i + (lane >> 5); float v = 0.f; if (src >= 0) v = __builtin_nontemporal_load(&W[(size_t)(k0 + kk) * Nsrc + src]); if (gk) v *= gk[k0 + kk]; scr[kk * 33 + (lane & 31)] = v; }
;     asm volatile("s_waitcnt lgkmcnt(0)" ::: "memory");
;     const int c = lane & 7;
; #pragma unroll
;     for (int j = 0; j < 4; ++j) { const int n = (lane >> 3) + 8 * j; const LAS float* s = scr + (8 * c) * 33 + n;
;         u32x4 o; o.x = pk2(s[0 * 33], s[1 * 33]); o.y = pk2(s[2 * 33], s[3 * 33]); o.z = pk2(s[4 * 33], s[5 * 33]); o.w = pk2(s[6 * 33], s[7 * 33]);
;         *(u32x4*)(WT + (size_t)(n0 + n) * K + k0 + 8 * c) = o; }
	s_add_u32 s8, s6, s19
	s_addc_u32 s9, s7, 0
	global_load_dword v32, v6, s[8:9] nt
	s_add_u32 s8, s8, s10
	s_addc_u32 s9, s9, 0
	global_load_dword v33, v6, s[8:9] nt
	s_add_u32 s8, s8, s10
	s_addc_u32 s9, s9, 0
	global_load_dword v34, v6, s[8:9] nt
	s_add_u32 s8, s8, s10
	s_addc_u32 s9, s9, 0
	global_load_dword v35, v6, s[8:9] nt
	s_add_u32 s8, s8, s10
	s_addc_u32 s9, s9, 0
	global_load_dword v36, v6, s[8:9] nt
	s_add_u32 s8, s8, s10
	s_addc_u32 s9, s9, 0
	global_load_dword v37, v6, s[8:9] nt
	s_add_u32 s8, s8, s10
	s_addc_u32 s9, s9, 0
	global_load_dword v38, v6, s[8:9] nt
	s_add_u32 s8, s8, s10
	s_addc_u32 s9, s9, 0
	global_load_dword v39, v6, s[8:9] nt
	s_add_u32 s8, s8, s10
	s_addc_u32 s9, s9, 0
	global_load_dword v40, v6, s[8:9] nt
	s_add_u32 s8, s8, s10
	s_addc_u32 s9, s9, 0
	global_load_dword v41, v6, s[8:9] nt
	s_add_u32 s8, s8, s10
	s_addc_u32 s9, s9, 0
	global_load_dword v42, v6, s[8:9] nt
	s_add_u32 s8, s8, s10
	s_addc_u32 s9, s9, 0
	global_load_dword v43, v6, s[8:9] nt
	s_add_u32 s8, s8, s10
	s_addc_u32 s9, s9, 0
	global_load_dword v44, v6, s[8:9] nt
	s_add_u32 s8, s8, s10
	s_addc_u32 s9, s9, 0
	global_load_dword v45, v6, s[8:9] nt
	s_add_u32 s8, s8, s10
	s_addc_u32 s9, s9, 0
	global_load_dword v46, v6, s[8:9] nt
	s_add_u32 s8, s8, s10
	s_addc_u32 s9, s9, 0
	global_load_dword v47, v6, s[8:9] nt
	s_add_u32 s8, s8, s10
	s_addc_u32 s9, s9, 0
	global_load_dword v48, v6, s[8:9] nt
	s_add_u32 s8, s8, s10
	s_addc_u32 s9, s9, 0
	global_load_dword v49, v6, s[8:9] nt
	s_add_u32 s8, s8, s10
	s_addc_u32 s9, s9, 0
	global_load_dword v50, v6, s[8:9] nt
	s_add_u32 s8, s8, s10
	s_addc_u32 s9, s9, 0
	global_load_dword v51, v6, s[8:9] nt
	s_add_u32 s8, s8, s10
	s_addc_u32 s9, s9, 0
	global_load_dword v52, v6, s[8:9] nt
	s_add_u32 s8, s8, s10
	s_addc_u32 s9, s9, 0
	global_load_dword v53, v6, s[8:9] nt
	s_add_u32 s8, s8, s10
	s_addc_u32 s9, s9, 0
	global_load_dword v54, v6, s[8:9] nt
	s_add_u32 s8, s8, s10
	s_addc_u32 s9, s9, 0
	global_load_dword v55, v6, s[8:9] nt
	s_add_u32 s8, s8, s10
	s_addc_u32 s9, s9, 0
	global_load_dword v56, v6, s[8:9] nt
	s_add_u32 s8, s8, s10
	s_addc_u32 s9, s9, 0
	global_load_dword v57, v6, s[8:9] nt
	s_add_u32 s8, s8, s10
	s_addc_u32 s9, s9, 0
	global_load_dword v58, v6, s[8:9] nt
	s_add_u32 s8, s8, s10
	s_addc_u32 s9, s9, 0
	global_load_dword v59, v6, s[8:9] nt
	s_add_u32 s8, s8, s10
	s_addc_u32 s9, s9, 0
	global_load_dword v60, v6, s[8:9] nt
	s_add_u32 s8, s8, s10
	s_addc_u32 s9, s9, 0
	global_load_dword v61, v6, s[8:9] nt
	s_add_u32 s8, s8, s10
	s_addc_u32 s9, s9, 0
	global_load_dword v62, v6, s[8:9] nt
	s_add_u32 s8, s8, s10
	s_addc_u32 s9, s9, 0
	global_load_dword v63, v6, s[8:9] nt
	s_mov_b64 s[30:31], s[26:27]
	s_waitcnt vmcnt(63)
	ds_write_b32 v4, v64
	s_waitcnt vmcnt(63)
	ds_write_b32 v4, v65 offset:264
	s_waitcnt vmcnt(63)
	ds_write_b32 v4, v66 offset:528
	s_waitcnt vmcnt(63)
	ds_write_b32 v4, v67 offset:792
	s_waitcnt vmcnt(63)
	ds_write_b32 v4, v68 offset:1056
	s_waitcnt vmcnt(62)
	ds_write_b32 v4, v69 offset:1320
	s_waitcnt vmcnt(61)
	ds_write_b32 v4, v70 offset:1584
	s_waitcnt vmcnt(60)
	ds_write_b32 v4, v71 offset:1848
	s_waitcnt vmcnt(59)
	ds_write_b32 v4, v72 offset:2112
	s_waitcnt vmcnt(58)
	ds_write_b32 v4, v73 offset:2376
	s_waitcnt vmcnt(57)
	ds_write_b32 v4, v74 offset:2640
	s_waitcnt vmcnt(56)
	ds_write_b32 v4, v75 offset:2904
	s_waitcnt vmcnt(55)
	ds_write_b32 v4, v76 offset:3168
	s_waitcnt vmcnt(54)
	ds_write_b32 v4, v77 offset:3432
	s_waitcnt vmcnt(53)
	ds_write_b32 v4, v78 offset:3696
	s_waitcnt vmcnt(52)
	ds_write_b32 v4, v79 offset:3960
	s_waitcnt vmcnt(51)
	ds_write_b32 v4, v80 offset:4224
	s_waitcnt vmcnt(50)
	ds_write_b32 v4, v81 offset:4488
	s_waitcnt vmcnt(49)
	ds_write_b32 v4, v82 offset:4752
	s_waitcnt vmcnt(48)
	ds_write_b32 v4, v83 offset:5016
	s_waitcnt vmcnt(47)
	ds_write_b32 v4, v84 offset:5280
	s_waitcnt vmcnt(46)
	ds_write_b32 v4, v85 offset:5544
	s_waitcnt vmcnt(45)
	ds_write_b32 v4, v86 offset:5808
	s_waitcnt vmcnt(44)
	ds_write_b32 v4, v87 offset:6072
	s_waitcnt vmcnt(43)
	ds_write_b32 v4, v88 offset:6336
	s_waitcnt vmcnt(42)
	ds_write_b32 v4, v89 offset:6600
	s_waitcnt vmcnt(41)
	ds_write_b32 v4, v90 offset:6864
	s_waitcnt vmcnt(40)
	ds_write_b32 v4, v91 offset:7128
	s_waitcnt vmcnt(39)
	ds_write_b32 v4, v92 offset:7392
	s_waitcnt vmcnt(38)
	ds_write_b32 v4, v93 offset:7656
	s_waitcnt vmcnt(37)
	ds_write_b32 v4, v94 offset:7920
	s_waitcnt vmcnt(36)
	ds_write_b32 v4, v95 offset:8184
	s_waitcnt lgkmcnt(0)
	ds_read2_b32 v[96:97], v5 offset0:0 offset1:8
	ds_read2_b32 v[98:99], v5 offset0:16 offset1:24
	ds_read2_b32 v[100:101], v5 offset0:33 offset1:41
	ds_read2_b32 v[102:103], v5 offset0:49 offset1:57
	ds_read2_b32 v[104:105], v5 offset0:66 offset1:74
	ds_read2_b32 v[106:107], v5 offset0:82 offset1:90
	ds_read2_b32 v[108:109], v5 offset0:99 offset1:107
	ds_read2_b32 v[110:111], v5 offset0:115 offset1:123
	ds_read2_b32 v[112:113], v5 offset0:132 offset1:140
	ds_read2_b32 v[114:115], v5 offset0:148 offset1:156
	ds_read2_b32 v[116:117], v5 offset0:165 offset1:173
	ds_read2_b32 v[118:119], v5 offset0:181 offset1:189
	ds_read2_b32 v[120:121], v5 offset0:198 offset1:206
	ds_read2_b32 v[122:123], v5 offset0:214 offset1:222
	ds_read2_b32 v[124:125], v5 offset0:231 offset1:239
	ds_read2_b32 v[126:127], v5 offset0:247 offset1:255
	s_waitcnt lgkmcnt(0)
	v_cvt_pk_bf16_f32 v12, v96, v100
	v_cvt_pk_bf16_f32 v13, v104, v108
	v_cvt_pk_bf16_f32 v14, v112, v116
	v_cvt_pk_bf16_f32 v15, v120, v124
	global_store_dwordx4 v9, v[12:15], s[30:31]
	s_add_u32 s30, s30, s28
	s_addc_u32 s31, s31, 0
	v_cvt_pk_bf16_f32 v16, v97, v101
	v_cvt_pk_bf16_f32 v17, v105, v109
	v_cvt_pk_bf16_f32 v18, v113, v117
	v_cvt_pk_bf16_f32 v19, v121, v125
	global_store_dwordx4 v9, v[16:19], s[30:31]
	s_add_u32 s30, s30, s28
	s_addc_u32 s31, s31, 0
	v_cvt_pk_bf16_f32 v12, v98, v102
	v_cvt_pk_bf16_f32 v13, v106, v110
	v_cvt_pk_bf16_f32 v14, v114, v118
	v_cvt_pk_bf16_f32 v15, v122, v126
	global_store_dwordx4 v9, v[12:15], s[30:31]
	s_add_u32 s30, s30, s28
	s_addc_u32 s31, s31, 0
	v_cvt_pk_bf16_f32 v16, v99, v103
	v_cvt_pk_bf16_f32 v17, v107, v111
	v_cvt_pk_bf16_f32 v18, v115, v119
	v_cvt_pk_bf16_f32 v19, v123, v127
	global_store_dwordx4 v9, v[16:19], s[30:31]
	s_mov_b32 s4, s5
	s_add_i32 s5, s4, 0x400
	s_cmp_gt_i32 s5, s33
	s_cbranch_scc1 .Lp1t_tail_a
; #define LAS __attribute__((address_space(3)))
; template <int KIND> __device__ __forceinline__ void tr_item(const float* __restrict__ W, int K, int Nsrc, const float* __restrict__ gk, bf16_t* WT, LAS float* scr, int item, int nblk, int lane) {
;     const int kb = item / nblk, nb = item - kb * nblk, k0 = 64 * kb, n0 = 32 * nb;
;     const int src = srcmap<KIND>(n0 + (lane & 31));
; #pragma unroll 8
;     for (int i = 0; i < 32; ++i) { const int kk = 2 * i + (lane >> 5); float v = 0.f; if (src >= 0) v = __builtin_nontemporal_load(&W[(size_t)(k0 + kk) * Nsrc + src]); if (gk) v *= gk[k0 + kk]; scr[kk * 33 + (lane & 31)] = v; }
	s_mov_b32 s16, 0x7580
	s_movk_i32 s15, 0x98
	s_mov_b32 s11, 13
	s_mov_b32 s12, 6
	s_mov_b32 s13, 11
	s_mov_b32 s14, 61603840
	s_cmpk_lt_u32 s5, 0x7580
	s_cselect_b32 s16, 0x7480, s16
	s_cselect_b32 s15, 0x88, s15
	s_cselect_b32 s11, 13, s11
	s_cselect_b32 s12, 6, s12
	s_cselect_b32 s13, 8, s13
	s_cselect_b32 s14, 61079552, s14
	s_cmpk_lt_u32 s5, 0x7480
	s_cselect_b32 s16, 0x5480, s16
	s_cselect_b32 s15, 0x78, s15
	s_cselect_b32 s11, 13, s11
	s_cselect_b32 s12, 6, s12
	s_cselect_b32 s13, 13, s13
	s_cselect_b32 s14, 44302336, s14
	s_cmpk_lt_u32 s5, 0x5480
	s_cselect_b32 s16, 0x3480, s16
	s_cselect_b32 s15, 0x70, s15
	s_cselect_b32 s11, 15, s11
	s_cselect_b32 s12, 8, s12
	s_cselect_b32 s13, 11, s13
	s_cselect_b32 s14, 27525120, s14
	s_cmpk_lt_u32 s5, 0x3480
	s_cselect_b32 s16, 0x2c80, s16
	s_cselect_b32 s15, 0x58, s15
	s_cselect_b32 s11, 13, s11
	s_cselect_b32 s12, 6, s12
	s_cselect_b32 s13, 11, s13
	s_cselect_b32 s14, 23330816, s14
	s_cmpk_lt_u32 s5, 0x2c80
	s_cselect_b32 s16, 0x2880, s16
	s_cselect_b32 s15, 0x50, s15
	s_cselect_b32 s11, 13, s11
	s_cselect_b32 s12, 6, s12
	s_cselect_b32 s13, 10, s13
	s_cselect_b32 s14, 21233664, s14
	s_cmpk_lt_u32 s5, 0x2880
	s_cselect_b32 s16, 0x2480, s16
	s_cselect_b32 s15, 0x48, s15
	s_cselect_b32 s11, 13, s11
	s_cselect_b32 s12, 6, s12
	s_cselect_b32 s13, 10, s13
	s_cselect_b32 s14, 19136512, s14
	s_load_dwordx2 s[6:7], s[0:1], s15
	s_sub_i32 s16, s5, s16
	s_lshl_b32 s19, 1, s12
	s_sub_i32 s19, s19, 1
	s_and_b32 s18, s16, s19
	s_lshr_b32 s17, s16, s12
	s_lshl_b32 s17, s17, 6
	s_lshl_b32 s19, s17, s11
	s_lshl_b32 s29, s18, 7
	s_add_u32 s19, s19, s29
	s_lshl_b32 s10, 2, s11
	v_lshlrev_b32_e32 v6, s11, v0
	v_add_u32_e32 v6, v6, v1
	s_lshl_b32 s29, s18, 5
	s_lshl_b32 s29, s29, s13
	s_add_u32 s29, s29, s17
	s_add_u32 s29, s29, s14
	s_lshl_b32 s29, s29, 1
	s_add_u32 s26, s20, s29
	s_addc_u32 s27, s21, 0
	s_lshl_b32 s28, 16, s13
	s_add_i32 s29, s13, 1
	v_lshlrev_b32_e32 v9, s29, v2
	v_add_u32_e32 v9, v9, v3
	s_waitcnt lgkmcnt(0)
	s_add_u32 s8, s6, s19
	s_addc_u32 s9, s7, 0
	global_load_dword v64, v6, s[8:9] nt
	s_add_u32 s8, s8, s10
	s_addc_u32 s9, s9, 0
	global_load_dword v65, v6, s[8:9] nt
	s_add_u32 s8, s8, s10
	s_addc_u32 s9, s9, 0
	global_load_dword v66, v6, s[8:9] nt
	s_add_u32 s8, s8, s10
	s_addc_u32 s9, s9, 0
	global_load_dword v67, v6, s[8:9] nt
	s_add_u32 s8, s8, s10
	s_addc_u32 s9, s9, 0
	global_load_dword v68, v6, s[8:9] nt
	s_add_u32 s8, s8, s10
	s_addc_u32 s9, s9, 0
	global_load_dword v69, v6, s[8:9] nt
	s_add_u32 s8, s8, s10
	s_addc_u32 s9, s9, 0
	global_load_dword v70, v6, s[8:9] nt
	s_add_u32 s8, s8, s10
	s_addc_u32 s9, s9, 0
	global_load_dword v71, v6, s[8:9] nt
	s_add_u32 s8, s8, s10
	s_addc_u32 s9, s9, 0
	global_load_dword v72, v6, s[8:9] nt
	s_add_u32 s8, s8, s10
	s_addc_u32 s9, s9, 0
	global_load_dword v73, v6, s[8:9] nt
	s_add_u32 s8, s8, s10
	s_addc_u32 s9, s9, 0
	global_load_dword v74, v6, s[8:9] nt
	s_add_u32 s8, s8, s10
	s_addc_u32 s9, s9, 0
	global_load_dword v75, v6, s[8:9] nt
	s_add_u32 s8, s8, s10
	s_addc_u32 s9, s9, 0
	global_load_dword v76, v6, s[8:9] nt
	s_add_u32 s8, s8, s10
	s_addc_u32 s9, s9, 0
	global_load_dword v77, v6, s[8:9] nt
	s_add_u32 s8, s8, s10
	s_addc_u32 s9, s9, 0
	global_load_dword v78, v6, s[8:9] nt
	s_add_u32 s8, s8, s10
	s_addc_u32 s9, s9, 0
	global_load_dword v79, v6, s[8:9] nt
	s_add_u32 s8, s8, s10
	s_addc_u32 s9, s9, 0
	global_load_dword v80, v6, s[8:9] nt
	s_add_u32 s8, s8, s10
	s_addc_u32 s9, s9, 0
	global_load_dword v81, v6, s[8:9] nt
	s_add_u32 s8, s8, s10
	s_addc_u32 s9, s9, 0
	global_load_dword v82, v6, s[8:9] nt
	s_add_u32 s8, s8, s10
	s_addc_u32 s9, s9, 0
	global_load_dword v83, v6, s[8:9] nt
	s_add_u32 s8, s8, s10
	s_addc_u32 s9, s9, 0
	global_load_dword v84, v6, s[8:9] nt
	s_add_u32 s8, s8, s10
	s_addc_u32 s9, s9, 0
	global_load_dword v85, v6, s[8:9] nt
	s_add_u32 s8, s8, s10
	s_addc_u32 s9, s9, 0
	global_load_dword v86, v6, s[8:9] nt
	s_add_u32 s8, s8, s10
	s_addc_u32 s9, s9, 0
	global_load_dword v87, v6, s[8:9] nt
	s_add_u32 s8, s8, s10
	s_addc_u32 s9, s9, 0
	global_load_dword v88, v6, s[8:9] nt
	s_add_u32 s8, s8, s10
	s_addc_u32 s9, s9, 0
	global_load_dword v89, v6, s[8:9] nt
	s_add_u32 s8, s8, s10
	s_addc_u32 s9, s9, 0
	global_load_dword v90, v6, s[8:9] nt
	s_add_u32 s8, s8, s10
	s_addc_u32 s9, s9, 0
	global_load_dword v91, v6, s[8:9] nt
	s_add_u32 s8, s8, s10
	s_addc_u32 s9, s9, 0
	global_load_dword v92, v6, s[8:9] nt
	s_add_u32 s8, s8, s10
	s_addc_u32 s9, s9, 0
	global_load_dword v93, v6, s[8:9] nt
	s_add_u32 s8, s8, s10
	s_addc_u32 s9, s9, 0
	global_load_dword v94, v6, s[8:9] nt
	s_add_u32 s8, s8, s10
	s_addc_u32 s9, s9, 0
	global_load_dword v95, v6, s[8:9] nt
	s_mov_b64 s[30:31], s[22:23]
	s_waitcnt vmcnt(63)
; #define LAS __attribute__((address_space(3)))
; __device__ __forceinline__ unsigned pk2(float lo, float hi) { return pg8::cvt_pk_bf16(lo, hi); }
; template <int KIND> __device__ __forceinline__ void tr_item(const float* __restrict__ W, int K, int Nsrc, const float* __restrict__ gk, bf16_t* WT, LAS float* scr, int item, int nblk, int lane) {
;     ...
;     for (int i = 0; i < 32; ++i) { const int kk = 2 * i + (lane >> 5); float v = 0.f; if (src >= 0) v = __builtin_nontemporal_load(&W[(size_t)(k0 + kk) * Nsrc + src]); if (gk) v *= gk[k0 + kk]; scr[kk * 33 + (lane & 31)] = v; }
;     asm volatile("s_waitcnt lgkmcnt(0)" ::: "memory");
;     const int c = lane & 7;
; #pragma unroll
;     for (int j = 0; j < 4; ++j) { const int n = (lane >> 3) + 8 * j; const LAS float* s = scr + (8 * c) * 33 + n;
;         u32x4 o; o.x = pk2(s[0 * 33], s[1 * 33]); o.y = pk2(s[2 * 33], s[3 * 33]); o.z = pk2(s[4 * 33], s[5 * 33]); o.w = pk2(s[6 * 33], s[7 * 33]);
;         *(u32x4*)(WT + (size_t)(n0 + n) * K + k0 + 8 * c) = o; }
	ds_write_b32 v4, v32
	s_waitcnt vmcnt(63)
	ds_write_b32 v4, v33 offset:264
	s_waitcnt vmcnt(63)
	ds_write_b32 v4, v34 offset:528
	s_waitcnt vmcnt(63)
	ds_write_b32 v4, v35 offset:792
	s_waitcnt vmcnt(63)
	ds_write_b32 v4, v36 offset:1056
	s_waitcnt vmcnt(62)
	ds_write_b32 v4, v37 offset:1320
	s_waitcnt vmcnt(61)
	ds_write_b32 v4, v38 offset:1584
	s_waitcnt vmcnt(60)
	ds_write_b32 v4, v39 offset:1848
	s_waitcnt vmcnt(59)
	ds_write_b32 v4, v40 offset:2112
	s_waitcnt vmcnt(58)
	ds_write_b32 v4, v41 offset:2376
	s_waitcnt vmcnt(57)
	ds_write_b32 v4, v42 offset:2640
	s_waitcnt vmcnt(56)
	ds_write_b32 v4, v43 offset:2904
	s_waitcnt vmcnt(55)
	ds_write_b32 v4, v44 offset:3168
	s_waitcnt vmcnt(54)
	ds_write_b32 v4, v45 offset:3432
	s_waitcnt vmcnt(53)
	ds_write_b32 v4, v46 offset:3696
	s_waitcnt vmcnt(52)
	ds_write_b32 v4, v47 offset:3960
	s_waitcnt vmcnt(51)
	ds_write_b32 v4, v48 offset:4224
	s_waitcnt vmcnt(50)
	ds_write_b32 v4, v49 offset:4488
	s_waitcnt vmcnt(49)
	ds_write_b32 v4, v50 offset:4752
	s_waitcnt vmcnt(48)
	ds_write_b32 v4, v51 offset:5016
	s_waitcnt vmcnt(47)
	ds_write_b32 v4, v52 offset:5280
	s_waitcnt vmcnt(46)
	ds_write_b32 v4, v53 offset:5544
	s_waitcnt vmcnt(45)
	ds_write_b32 v4, v54 offset:5808
	s_waitcnt vmcnt(44)
	ds_write_b32 v4, v55 offset:6072
	s_waitcnt vmcnt(43)
	ds_write_b32 v4, v56 offset:6336
	s_waitcnt vmcnt(42)
	ds_write_b32 v4, v57 offset:6600
	s_waitcnt vmcnt(41)
	ds_write_b32 v4, v58 offset:6864
	s_waitcnt vmcnt(40)
	ds_write_b32 v4, v59 offset:7128
	s_waitcnt vmcnt(39)
	ds_write_b32 v4, v60 offset:7392
	s_waitcnt vmcnt(38)
	ds_write_b32 v4, v61 offset:7656
	s_waitcnt vmcnt(37)
	ds_write_b32 v4, v62 offset:7920
	s_waitcnt vmcnt(36)
	ds_write_b32 v4, v63 offset:8184
	s_waitcnt lgkmcnt(0)
	ds_read2_b32 v[96:97], v5 offset0:0 offset1:8
	ds_read2_b32 v[98:99], v5 offset0:16 offset1:24
	ds_read2_b32 v[100:101], v5 offset0:33 offset1:41
	ds_read2_b32 v[102:103], v5 offset0:49 offset1:57
	ds_read2_b32 v[104:105], v5 offset0:66 offset1:74
	ds_read2_b32 v[106:107], v5 offset0:82 offset1:90
	ds_read2_b32 v[108:109], v5 offset0:99 offset1:107
	ds_read2_b32 v[110:111], v5 offset0:115 offset1:123
	ds_read2_b32 v[112:113], v5 offset0:132 offset1:140
	ds_read2_b32 v[114:115], v5 offset0:148 offset1:156
	ds_read2_b32 v[116:117], v5 offset0:165 offset1:173
	ds_read2_b32 v[118:119], v5 offset0:181 offset1:189
	ds_read2_b32 v[120:121], v5 offset0:198 offset1:206
	ds_read2_b32 v[122:123], v5 offset0:214 offset1:222
	ds_read2_b32 v[124:125], v5 offset0:231 offset1:239
	ds_read2_b32 v[126:127], v5 offset0:247 offset1:255
	s_waitcnt lgkmcnt(0)
	v_cvt_pk_bf16_f32 v12, v96, v100
	v_cvt_pk_bf16_f32 v13, v104, v108
	v_cvt_pk_bf16_f32 v14, v112, v116
	v_cvt_pk_bf16_f32 v15, v120, v124
	global_store_dwordx4 v8, v[12:15], s[30:31]
	s_add_u32 s30, s30, s24
	s_addc_u32 s31, s31, 0
	v_cvt_pk_bf16_f32 v16, v97, v101
	v_cvt_pk_bf16_f32 v17, v105, v109
	v_cvt_pk_bf16_f32 v18, v113, v117
	v_cvt_pk_bf16_f32 v19, v121, v125
	global_store_dwordx4 v8, v[16:19], s[30:31]
	s_add_u32 s30, s30, s24
	s_addc_u32 s31, s31, 0
	v_cvt_pk_bf16_f32 v12, v98, v102
	v_cvt_pk_bf16_f32 v13, v106, v110
	v_cvt_pk_bf16_f32 v14, v114, v118
	v_cvt_pk_bf16_f32 v15, v122, v126
	global_store_dwordx4 v8, v[12:15], s[30:31]
	s_add_u32 s30, s30, s24
	s_addc_u32 s31, s31, 0
	v_cvt_pk_bf16_f32 v16, v99, v103
	v_cvt_pk_bf16_f32 v17, v107, v111
	v_cvt_pk_bf16_f32 v18, v115, v119
	v_cvt_pk_bf16_f32 v19, v123, v127
	global_store_dwordx4 v8, v[16:19], s[30:31]
	s_mov_b32 s4, s5
	s_branch .Lp1t_loop
